# P7 router: expert loop unrolled by 4 with interleaved bpermute reduction chains (plus NA batching and phase-split GEMM loops)
# speedup vs baseline: 1.0598x; 1.0065x over previous
; __global__ void __launch_bounds__(NTHR) fwd_megakernel(Params p) {
;     ...
;       for (int e = 0; e < 16; ++e) {
;         float a4[4] = {0.f, 0.f, 0.f, 0.f};
; #pragma unroll
;         for (int i = 0; i < 4; ++i) {
;           const float4 w = *(const float4*)(wr + e * 1028 + i * 256 + lane * 4);
; #pragma unroll
;           for (int rr = 0; rr < 4; ++rr)
;             a4[rr] += yv[rr][i * 4] * w.x + yv[rr][i * 4 + 1] * w.y + yv[rr][i * 4 + 2] * w.z + yv[rr][i * 4 + 3] * w.w;
;         }
.LBB0_1023:
.Lrt_loop:
	v_add_u32_e32 v1, s14, v102
	ds_read_b128 v[20:23], v1
	ds_read_b128 v[32:35], v1 offset:1024
	ds_read_b128 v[130:133], v1 offset:2048
	ds_read_b128 v[134:137], v1 offset:3072
	s_waitcnt lgkmcnt(3)
	v_mul_f32_e32 v1, v21, v118
	v_mul_f32_e32 v5, v21, v121
	v_mul_f32_e32 v100, v21, v61
	v_mul_f32_e32 v101, v21, v65
	s_waitcnt lgkmcnt(2)
	v_mul_f32_e32 v126, v33, v67
	v_mul_f32_e32 v127, v33, v95
	v_mul_f32_e32 v129, v33, v125
	v_mul_f32_e32 v138, v33, v57
	s_waitcnt lgkmcnt(0)
	v_mov_b32_e32 v7, v134
	v_mov_b32_e32 v134, v131
	v_fmac_f32_e32 v1, v20, v117
	v_fmac_f32_e32 v5, v20, v91
	v_fmac_f32_e32 v100, v20, v60
	v_fmac_f32_e32 v101, v20, v64
	v_mov_b32_e32 v6, v130
	v_fmac_f32_e32 v126, v32, v66
	v_fmac_f32_e32 v127, v32, v94
	v_fmac_f32_e32 v129, v32, v124
	v_fmac_f32_e32 v138, v32, v56
	v_pk_mul_f32 v[20:21], v[134:135], v[24:25]
	v_pk_mul_f32 v[32:33], v[134:135], v[28:29]
	v_pk_mul_f32 v[58:59], v[134:135], v[36:37]
	v_pk_mul_f32 v[96:97], v[134:135], v[44:45]
	v_fmac_f32_e32 v1, v22, v119
	v_fmac_f32_e32 v5, v22, v122
	v_fmac_f32_e32 v100, v22, v62
	v_fmac_f32_e32 v101, v22, v10
	v_mov_b32_e32 v12, v132
	v_mov_b32_e32 v13, v136
	v_fmac_f32_e32 v126, v34, v92
	v_fmac_f32_e32 v127, v34, v98
	v_fmac_f32_e32 v129, v34, v54
	v_fmac_f32_e32 v138, v34, v42
	v_pk_fma_f32 v[20:21], v[6:7], v[8:9], v[20:21]
	v_pk_fma_f32 v[32:33], v[6:7], v[16:17], v[32:33]
	v_pk_fma_f32 v[58:59], v[6:7], v[30:31], v[58:59]
	v_pk_fma_f32 v[6:7], v[6:7], v[40:41], v[96:97]
	v_fmac_f32_e32 v1, v23, v120
	v_fmac_f32_e32 v5, v23, v123
	v_fmac_f32_e32 v100, v23, v63
	v_fmac_f32_e32 v101, v23, v11
	v_mov_b32_e32 v136, v133
	v_fmac_f32_e32 v126, v35, v93
	v_fmac_f32_e32 v127, v35, v99
	v_fmac_f32_e32 v129, v35, v55
	v_fmac_f32_e32 v138, v35, v43
	v_pk_fma_f32 v[20:21], v[12:13], v[26:27], v[20:21]
	v_pk_fma_f32 v[22:23], v[12:13], v[18:19], v[32:33]
	v_pk_fma_f32 v[32:33], v[12:13], v[38:39], v[58:59]
	v_pk_fma_f32 v[6:7], v[12:13], v[46:47], v[6:7]
	v_add_f32_e32 v1, 0, v1
	v_add_f32_e32 v5, 0, v5
	v_add_f32_e32 v34, 0, v100
	v_add_f32_e32 v35, 0, v101
	v_pk_fma_f32 v[12:13], v[136:137], v[48:49], v[20:21]
	v_pk_fma_f32 v[20:21], v[136:137], v[50:51], v[22:23]
	v_pk_fma_f32 v[22:23], v[136:137], v[52:53], v[32:33]
	v_pk_fma_f32 v[6:7], v[136:137], v[14:15], v[6:7]
	v_add_f32_e32 v1, v1, v126
	v_add_f32_e32 v5, v5, v127
	v_add_f32_e32 v32, v34, v129
	v_add_f32_e32 v33, v35, v138
	v_add_f32_e32 v1, v1, v12
	v_add_f32_e32 v5, v5, v20
	v_add_f32_e32 v12, v32, v22
	v_add_f32_e32 v6, v33, v6
	v_add_f32_e32 v1, v1, v13
	v_add_f32_e32 v5, v5, v21
	v_add_f32_e32 v12, v12, v23
	v_add_f32_e32 v6, v6, v7
	v_mov_b32_e32 v236, v1
	v_mov_b32_e32 v237, v5
	v_mov_b32_e32 v238, v12
	v_mov_b32_e32 v239, v6
	s_addk_i32 s14, 0x1010
	v_add_u32_e32 v1, s14, v102
	ds_read_b128 v[20:23], v1
	ds_read_b128 v[32:35], v1 offset:1024
	ds_read_b128 v[130:133], v1 offset:2048
	ds_read_b128 v[134:137], v1 offset:3072
	s_waitcnt lgkmcnt(3)
	v_mul_f32_e32 v1, v21, v118
	v_mul_f32_e32 v5, v21, v121
	v_mul_f32_e32 v100, v21, v61
	v_mul_f32_e32 v101, v21, v65
	s_waitcnt lgkmcnt(2)
	v_mul_f32_e32 v126, v33, v67
	v_mul_f32_e32 v127, v33, v95
	v_mul_f32_e32 v129, v33, v125
	v_mul_f32_e32 v138, v33, v57
	s_waitcnt lgkmcnt(0)
	v_mov_b32_e32 v7, v134
	v_mov_b32_e32 v134, v131
	v_fmac_f32_e32 v1, v20, v117
	v_fmac_f32_e32 v5, v20, v91
	v_fmac_f32_e32 v100, v20, v60
	v_fmac_f32_e32 v101, v20, v64
	v_mov_b32_e32 v6, v130
	v_fmac_f32_e32 v126, v32, v66
	v_fmac_f32_e32 v127, v32, v94
	v_fmac_f32_e32 v129, v32, v124
	v_fmac_f32_e32 v138, v32, v56
	v_pk_mul_f32 v[20:21], v[134:135], v[24:25]
	v_pk_mul_f32 v[32:33], v[134:135], v[28:29]
	v_pk_mul_f32 v[58:59], v[134:135], v[36:37]
	v_pk_mul_f32 v[96:97], v[134:135], v[44:45]
	v_fmac_f32_e32 v1, v22, v119
	v_fmac_f32_e32 v5, v22, v122
	v_fmac_f32_e32 v100, v22, v62
	v_fmac_f32_e32 v101, v22, v10
	v_mov_b32_e32 v12, v132
	v_mov_b32_e32 v13, v136
	v_fmac_f32_e32 v126, v34, v92
	v_fmac_f32_e32 v127, v34, v98
	v_fmac_f32_e32 v129, v34, v54
	v_fmac_f32_e32 v138, v34, v42
	v_pk_fma_f32 v[20:21], v[6:7], v[8:9], v[20:21]
	v_pk_fma_f32 v[32:33], v[6:7], v[16:17], v[32:33]
	v_pk_fma_f32 v[58:59], v[6:7], v[30:31], v[58:59]
	v_pk_fma_f32 v[6:7], v[6:7], v[40:41], v[96:97]
	v_fmac_f32_e32 v1, v23, v120
	v_fmac_f32_e32 v5, v23, v123
	v_fmac_f32_e32 v100, v23, v63
	v_fmac_f32_e32 v101, v23, v11
	v_mov_b32_e32 v136, v133
	v_fmac_f32_e32 v126, v35, v93
	v_fmac_f32_e32 v127, v35, v99
	v_fmac_f32_e32 v129, v35, v55
	v_fmac_f32_e32 v138, v35, v43
	v_pk_fma_f32 v[20:21], v[12:13], v[26:27], v[20:21]
	v_pk_fma_f32 v[22:23], v[12:13], v[18:19], v[32:33]
	v_pk_fma_f32 v[32:33], v[12:13], v[38:39], v[58:59]
	v_pk_fma_f32 v[6:7], v[12:13], v[46:47], v[6:7]
	v_add_f32_e32 v1, 0, v1
	v_add_f32_e32 v5, 0, v5
	v_add_f32_e32 v34, 0, v100
	v_add_f32_e32 v35, 0, v101
	v_pk_fma_f32 v[12:13], v[136:137], v[48:49], v[20:21]
	v_pk_fma_f32 v[20:21], v[136:137], v[50:51], v[22:23]
	v_pk_fma_f32 v[22:23], v[136:137], v[52:53], v[32:33]
	v_pk_fma_f32 v[6:7], v[136:137], v[14:15], v[6:7]
	v_add_f32_e32 v1, v1, v126
	v_add_f32_e32 v5, v5, v127
	v_add_f32_e32 v32, v34, v129
	v_add_f32_e32 v33, v35, v138
	v_add_f32_e32 v1, v1, v12
	v_add_f32_e32 v5, v5, v20
	v_add_f32_e32 v12, v32, v22
	v_add_f32_e32 v6, v33, v6
	v_add_f32_e32 v1, v1, v13
	v_add_f32_e32 v5, v5, v21
	v_add_f32_e32 v12, v12, v23
	v_add_f32_e32 v6, v6, v7
	v_mov_b32_e32 v241, v1
	v_mov_b32_e32 v242, v5
	v_mov_b32_e32 v243, v12
	v_mov_b32_e32 v244, v6
	s_addk_i32 s14, 0x1010
	v_add_u32_e32 v1, s14, v102
	ds_read_b128 v[20:23], v1
	ds_read_b128 v[32:35], v1 offset:1024
	ds_read_b128 v[130:133], v1 offset:2048
	ds_read_b128 v[134:137], v1 offset:3072
	s_waitcnt lgkmcnt(3)
; __global__ void __launch_bounds__(NTHR) fwd_megakernel(Params p) {
;     ...
;       for (int e = 0; e < 16; ++e) {
;         float a4[4] = {0.f, 0.f, 0.f, 0.f};
; #pragma unroll
;         for (int i = 0; i < 4; ++i) {
;           const float4 w = *(const float4*)(wr + e * 1028 + i * 256 + lane * 4);
; #pragma unroll
;           for (int rr = 0; rr < 4; ++rr)
;             a4[rr] += yv[rr][i * 4] * w.x + yv[rr][i * 4 + 1] * w.y + yv[rr][i * 4 + 2] * w.z + yv[rr][i * 4 + 3] * w.w;
;         }
;         float r2[2];
;         { const bool hi = lane & 1;
;           const float s0 = hi ? a4[0] : a4[1], k0 = hi ? a4[1] : a4[0];
;           const float s1 = hi ? a4[2] : a4[3], k1 = hi ? a4[3] : a4[2];
;           r2[0] = k0 + __shfl_xor(s0, 1); r2[1] = k1 + __shfl_xor(s1, 1); }
	v_mul_f32_e32 v1, v21, v118
	v_mul_f32_e32 v5, v21, v121
	v_mul_f32_e32 v100, v21, v61
	v_mul_f32_e32 v101, v21, v65
	s_waitcnt lgkmcnt(2)
	v_mul_f32_e32 v126, v33, v67
	v_mul_f32_e32 v127, v33, v95
	v_mul_f32_e32 v129, v33, v125
	v_mul_f32_e32 v138, v33, v57
	s_waitcnt lgkmcnt(0)
	v_mov_b32_e32 v7, v134
	v_mov_b32_e32 v134, v131
	v_fmac_f32_e32 v1, v20, v117
	v_fmac_f32_e32 v5, v20, v91
	v_fmac_f32_e32 v100, v20, v60
	v_fmac_f32_e32 v101, v20, v64
	v_mov_b32_e32 v6, v130
	v_fmac_f32_e32 v126, v32, v66
	v_fmac_f32_e32 v127, v32, v94
	v_fmac_f32_e32 v129, v32, v124
	v_fmac_f32_e32 v138, v32, v56
	v_pk_mul_f32 v[20:21], v[134:135], v[24:25]
	v_pk_mul_f32 v[32:33], v[134:135], v[28:29]
	v_pk_mul_f32 v[58:59], v[134:135], v[36:37]
	v_pk_mul_f32 v[96:97], v[134:135], v[44:45]
	v_fmac_f32_e32 v1, v22, v119
	v_fmac_f32_e32 v5, v22, v122
	v_fmac_f32_e32 v100, v22, v62
	v_fmac_f32_e32 v101, v22, v10
	v_mov_b32_e32 v12, v132
	v_mov_b32_e32 v13, v136
	v_fmac_f32_e32 v126, v34, v92
	v_fmac_f32_e32 v127, v34, v98
	v_fmac_f32_e32 v129, v34, v54
	v_fmac_f32_e32 v138, v34, v42
	v_pk_fma_f32 v[20:21], v[6:7], v[8:9], v[20:21]
	v_pk_fma_f32 v[32:33], v[6:7], v[16:17], v[32:33]
	v_pk_fma_f32 v[58:59], v[6:7], v[30:31], v[58:59]
	v_pk_fma_f32 v[6:7], v[6:7], v[40:41], v[96:97]
	v_fmac_f32_e32 v1, v23, v120
	v_fmac_f32_e32 v5, v23, v123
	v_fmac_f32_e32 v100, v23, v63
	v_fmac_f32_e32 v101, v23, v11
	v_mov_b32_e32 v136, v133
	v_fmac_f32_e32 v126, v35, v93
	v_fmac_f32_e32 v127, v35, v99
	v_fmac_f32_e32 v129, v35, v55
	v_fmac_f32_e32 v138, v35, v43
	v_pk_fma_f32 v[20:21], v[12:13], v[26:27], v[20:21]
	v_pk_fma_f32 v[22:23], v[12:13], v[18:19], v[32:33]
	v_pk_fma_f32 v[32:33], v[12:13], v[38:39], v[58:59]
	v_pk_fma_f32 v[6:7], v[12:13], v[46:47], v[6:7]
	v_add_f32_e32 v1, 0, v1
	v_add_f32_e32 v5, 0, v5
	v_add_f32_e32 v34, 0, v100
	v_add_f32_e32 v35, 0, v101
	v_pk_fma_f32 v[12:13], v[136:137], v[48:49], v[20:21]
	v_pk_fma_f32 v[20:21], v[136:137], v[50:51], v[22:23]
	v_pk_fma_f32 v[22:23], v[136:137], v[52:53], v[32:33]
	v_pk_fma_f32 v[6:7], v[136:137], v[14:15], v[6:7]
	v_add_f32_e32 v1, v1, v126
	v_add_f32_e32 v5, v5, v127
	v_add_f32_e32 v32, v34, v129
	v_add_f32_e32 v33, v35, v138
	v_add_f32_e32 v1, v1, v12
	v_add_f32_e32 v5, v5, v20
	v_add_f32_e32 v12, v32, v22
	v_add_f32_e32 v6, v33, v6
	v_add_f32_e32 v1, v1, v13
	v_add_f32_e32 v5, v5, v21
	v_add_f32_e32 v12, v12, v23
	v_add_f32_e32 v6, v6, v7
	v_mov_b32_e32 v246, v1
	v_mov_b32_e32 v247, v5
	v_mov_b32_e32 v248, v12
	v_mov_b32_e32 v249, v6
	s_addk_i32 s14, 0x1010
	v_add_u32_e32 v1, s14, v102
	ds_read_b128 v[20:23], v1
	ds_read_b128 v[32:35], v1 offset:1024
	ds_read_b128 v[130:133], v1 offset:2048
	ds_read_b128 v[134:137], v1 offset:3072
	s_waitcnt lgkmcnt(3)
	v_mul_f32_e32 v1, v21, v118
	v_mul_f32_e32 v5, v21, v121
	v_mul_f32_e32 v100, v21, v61
	v_mul_f32_e32 v101, v21, v65
	s_waitcnt lgkmcnt(2)
	v_mul_f32_e32 v126, v33, v67
	v_mul_f32_e32 v127, v33, v95
	v_mul_f32_e32 v129, v33, v125
	v_mul_f32_e32 v138, v33, v57
	s_waitcnt lgkmcnt(0)
	v_mov_b32_e32 v7, v134
	v_mov_b32_e32 v134, v131
	v_fmac_f32_e32 v1, v20, v117
	v_fmac_f32_e32 v5, v20, v91
	v_fmac_f32_e32 v100, v20, v60
	v_fmac_f32_e32 v101, v20, v64
	v_mov_b32_e32 v6, v130
	v_fmac_f32_e32 v126, v32, v66
	v_fmac_f32_e32 v127, v32, v94
	v_fmac_f32_e32 v129, v32, v124
	v_fmac_f32_e32 v138, v32, v56
	v_pk_mul_f32 v[20:21], v[134:135], v[24:25]
	v_pk_mul_f32 v[32:33], v[134:135], v[28:29]
	v_pk_mul_f32 v[58:59], v[134:135], v[36:37]
	v_pk_mul_f32 v[96:97], v[134:135], v[44:45]
	v_fmac_f32_e32 v1, v22, v119
	v_fmac_f32_e32 v5, v22, v122
	v_fmac_f32_e32 v100, v22, v62
	v_fmac_f32_e32 v101, v22, v10
	v_mov_b32_e32 v12, v132
	v_mov_b32_e32 v13, v136
	v_fmac_f32_e32 v126, v34, v92
	v_fmac_f32_e32 v127, v34, v98
	v_fmac_f32_e32 v129, v34, v54
	v_fmac_f32_e32 v138, v34, v42
	v_pk_fma_f32 v[20:21], v[6:7], v[8:9], v[20:21]
	v_pk_fma_f32 v[32:33], v[6:7], v[16:17], v[32:33]
	v_pk_fma_f32 v[58:59], v[6:7], v[30:31], v[58:59]
	v_pk_fma_f32 v[6:7], v[6:7], v[40:41], v[96:97]
	v_fmac_f32_e32 v1, v23, v120
	v_fmac_f32_e32 v5, v23, v123
	v_fmac_f32_e32 v100, v23, v63
	v_fmac_f32_e32 v101, v23, v11
	v_mov_b32_e32 v136, v133
	v_fmac_f32_e32 v126, v35, v93
	v_fmac_f32_e32 v127, v35, v99
	v_fmac_f32_e32 v129, v35, v55
	v_fmac_f32_e32 v138, v35, v43
	v_pk_fma_f32 v[20:21], v[12:13], v[26:27], v[20:21]
	v_pk_fma_f32 v[22:23], v[12:13], v[18:19], v[32:33]
	v_pk_fma_f32 v[32:33], v[12:13], v[38:39], v[58:59]
	v_pk_fma_f32 v[6:7], v[12:13], v[46:47], v[6:7]
	v_add_f32_e32 v1, 0, v1
	v_add_f32_e32 v5, 0, v5
	v_add_f32_e32 v34, 0, v100
	v_add_f32_e32 v35, 0, v101
	v_pk_fma_f32 v[12:13], v[136:137], v[48:49], v[20:21]
	v_pk_fma_f32 v[20:21], v[136:137], v[50:51], v[22:23]
	v_pk_fma_f32 v[22:23], v[136:137], v[52:53], v[32:33]
	v_pk_fma_f32 v[6:7], v[136:137], v[14:15], v[6:7]
	v_add_f32_e32 v1, v1, v126
	v_add_f32_e32 v5, v5, v127
	v_add_f32_e32 v32, v34, v129
	v_add_f32_e32 v33, v35, v138
	v_add_f32_e32 v1, v1, v12
	v_add_f32_e32 v5, v5, v20
	v_add_f32_e32 v12, v32, v22
	v_add_f32_e32 v6, v33, v6
	v_add_f32_e32 v1, v1, v13
	v_add_f32_e32 v5, v5, v21
	v_add_f32_e32 v12, v12, v23
	v_add_f32_e32 v6, v6, v7
	v_mov_b32_e32 v251, v1
	v_mov_b32_e32 v252, v5
	v_mov_b32_e32 v253, v12
	v_mov_b32_e32 v254, v6
	s_addk_i32 s14, 0x1010
	v_cndmask_b32_e64 v240, v236, v237, s[10:11]
	v_cndmask_b32_e64 v236, v237, v236, s[10:11]
	v_cndmask_b32_e64 v237, v238, v239, s[10:11]
	v_cndmask_b32_e64 v239, v239, v238, s[10:11]
	v_cndmask_b32_e64 v245, v241, v242, s[10:11]
	v_cndmask_b32_e64 v241, v242, v241, s[10:11]
	v_cndmask_b32_e64 v242, v243, v244, s[10:11]
	v_cndmask_b32_e64 v244, v244, v243, s[10:11]
	v_cndmask_b32_e64 v250, v246, v247, s[10:11]
	v_cndmask_b32_e64 v246, v247, v246, s[10:11]
	v_cndmask_b32_e64 v247, v248, v249, s[10:11]
	v_cndmask_b32_e64 v249, v249, v248, s[10:11]
	v_cndmask_b32_e64 v255, v251, v252, s[10:11]
	v_cndmask_b32_e64 v251, v252, v251, s[10:11]
	v_cndmask_b32_e64 v252, v253, v254, s[10:11]
	v_cndmask_b32_e64 v254, v254, v253, s[10:11]
	ds_bpermute_b32 v240, v108, v240
	ds_bpermute_b32 v237, v108, v237
	ds_bpermute_b32 v245, v108, v245
	ds_bpermute_b32 v242, v108, v242
	ds_bpermute_b32 v250, v108, v250
	ds_bpermute_b32 v247, v108, v247
	ds_bpermute_b32 v255, v108, v255
	ds_bpermute_b32 v252, v108, v252
	s_waitcnt lgkmcnt(0)
; __global__ void __launch_bounds__(NTHR) fwd_megakernel(Params p) {
;     ...
;         float r2[2];
;         { const bool hi = lane & 1;
;           const float s0 = hi ? a4[0] : a4[1], k0 = hi ? a4[1] : a4[0];
;           const float s1 = hi ? a4[2] : a4[3], k1 = hi ? a4[3] : a4[2];
;           r2[0] = k0 + __shfl_xor(s0, 1); r2[1] = k1 + __shfl_xor(s1, 1); }
;         float r1;
;         { const bool hi = lane & 2;
;           const float s0 = hi ? r2[0] : r2[1], k0 = hi ? r2[1] : r2[0];
;           r1 = k0 + __shfl_xor(s0, 2); }
;         r1 += __shfl_xor(r1, 4); r1 += __shfl_xor(r1, 8); r1 += __shfl_xor(r1, 16); r1 += __shfl_xor(r1, 32);
; #pragma unroll
;         for (int rr = 0; rr < 4; ++rr) {
;           const float val = __shfl(r1, rr);
;           if (lane == e) mine[rr] = val;
;         }
;       }
; #pragma unroll
;       for (int rr = 0; rr < 4; ++rr) {
;         float lgv = (lane < 16) ? mine[rr] : -INFINITY;
;         float mxv = lgv;
; #pragma unroll
;         for (int o = 8; o > 0; o >>= 1) mxv = fmaxf(mxv, __shfl_xor(mxv, o));
;         mxv = __shfl(mxv, 0);
;         const float ex = (lane < 16) ? expf(lgv - mxv) : 0.f;
;         float den = ex;
; #pragma unroll
;         for (int o = 8; o > 0; o >>= 1) den += __shfl_xor(den, o);
;         den = __shfl(den, 0);
;         const int t = (row0 + rr) & 2047;
;         if (lane < 16) aff[((size_t)(b * 16 + lane)) * 2048 + t] = ex / den;
;       }
	v_add_f32_e32 v236, v236, v240
	v_add_f32_e32 v237, v239, v237
	v_add_f32_e32 v241, v241, v245
	v_add_f32_e32 v242, v244, v242
	v_add_f32_e32 v246, v246, v250
	v_add_f32_e32 v247, v249, v247
	v_add_f32_e32 v251, v251, v255
	v_add_f32_e32 v252, v254, v252
	v_cndmask_b32_e64 v239, v236, v237, s[12:13]
	v_cndmask_b32_e64 v236, v237, v236, s[12:13]
	v_cndmask_b32_e64 v244, v241, v242, s[12:13]
	v_cndmask_b32_e64 v241, v242, v241, s[12:13]
	v_cndmask_b32_e64 v249, v246, v247, s[12:13]
	v_cndmask_b32_e64 v246, v247, v246, s[12:13]
	v_cndmask_b32_e64 v254, v251, v252, s[12:13]
	v_cndmask_b32_e64 v251, v252, v251, s[12:13]
	ds_bpermute_b32 v237, v107, v239
	ds_bpermute_b32 v242, v107, v244
	ds_bpermute_b32 v247, v107, v249
	ds_bpermute_b32 v252, v107, v254
	s_waitcnt lgkmcnt(0)
	v_add_f32_e32 v236, v236, v237
	v_add_f32_e32 v241, v241, v242
	v_add_f32_e32 v246, v246, v247
	v_add_f32_e32 v251, v251, v252
	ds_bpermute_b32 v237, v106, v236
	ds_bpermute_b32 v242, v106, v241
	ds_bpermute_b32 v247, v106, v246
	ds_bpermute_b32 v252, v106, v251
	s_waitcnt lgkmcnt(0)
	v_add_f32_e32 v236, v236, v237
	v_add_f32_e32 v241, v241, v242
	v_add_f32_e32 v246, v246, v247
	v_add_f32_e32 v251, v251, v252
	ds_bpermute_b32 v237, v105, v236
	ds_bpermute_b32 v242, v105, v241
	ds_bpermute_b32 v247, v105, v246
	ds_bpermute_b32 v252, v105, v251
	s_waitcnt lgkmcnt(0)
	v_add_f32_e32 v236, v236, v237
	v_add_f32_e32 v241, v241, v242
	v_add_f32_e32 v246, v246, v247
	v_add_f32_e32 v251, v251, v252
	ds_bpermute_b32 v237, v104, v236
	ds_bpermute_b32 v242, v104, v241
	ds_bpermute_b32 v247, v104, v246
	ds_bpermute_b32 v252, v104, v251
	s_waitcnt lgkmcnt(0)
	v_add_f32_e32 v236, v236, v237
	v_add_f32_e32 v241, v241, v242
	v_add_f32_e32 v246, v246, v247
	v_add_f32_e32 v251, v251, v252
	ds_bpermute_b32 v237, v103, v236
	ds_bpermute_b32 v242, v103, v241
	ds_bpermute_b32 v247, v103, v246
	ds_bpermute_b32 v252, v103, v251
	s_waitcnt lgkmcnt(0)
	v_add_f32_e32 v236, v236, v237
	v_add_f32_e32 v241, v241, v242
	v_add_f32_e32 v246, v246, v247
	v_add_f32_e32 v251, v251, v252
	ds_bpermute_b32 v237, v109, v236
	ds_bpermute_b32 v239, v110, v236
	ds_bpermute_b32 v240, v111, v236
	ds_bpermute_b32 v238, v112, v236
	ds_bpermute_b32 v242, v109, v241
	ds_bpermute_b32 v244, v110, v241
	ds_bpermute_b32 v245, v111, v241
	ds_bpermute_b32 v243, v112, v241
	ds_bpermute_b32 v247, v109, v246
	ds_bpermute_b32 v249, v110, v246
	ds_bpermute_b32 v250, v111, v246
	ds_bpermute_b32 v248, v112, v246
	ds_bpermute_b32 v252, v109, v251
	ds_bpermute_b32 v254, v110, v251
	ds_bpermute_b32 v255, v111, v251
	ds_bpermute_b32 v253, v112, v251
	s_waitcnt lgkmcnt(0)
	s_add_i32 s99, s14, 0xffffbfc0
	v_cmp_eq_u32_e32 vcc, s99, v114
	s_nop 1
	v_cndmask_b32_e32 v0, v0, v237, vcc
	v_cndmask_b32_e32 v4, v4, v239, vcc
	v_cndmask_b32_e32 v3, v3, v240, vcc
	v_cndmask_b32_e32 v2, v2, v238, vcc
	s_add_i32 s99, s14, 0xffffcfd0
	v_cmp_eq_u32_e32 vcc, s99, v114
	s_nop 1
	v_cndmask_b32_e32 v0, v0, v242, vcc
	v_cndmask_b32_e32 v4, v4, v244, vcc
	v_cndmask_b32_e32 v3, v3, v245, vcc
	v_cndmask_b32_e32 v2, v2, v243, vcc
	s_add_i32 s99, s14, 0xffffdfe0
	v_cmp_eq_u32_e32 vcc, s99, v114
	s_nop 1
	v_cndmask_b32_e32 v0, v0, v247, vcc
	v_cndmask_b32_e32 v4, v4, v249, vcc
	v_cndmask_b32_e32 v3, v3, v250, vcc
	v_cndmask_b32_e32 v2, v2, v248, vcc
	s_add_i32 s99, s14, 0xffffeff0
	v_cmp_eq_u32_e32 vcc, s99, v114
	s_nop 1
	v_cndmask_b32_e32 v0, v0, v252, vcc
	v_cndmask_b32_e32 v4, v4, v254, vcc
	v_cndmask_b32_e32 v3, v3, v255, vcc
	v_cndmask_b32_e32 v2, v2, v253, vcc
	s_cmp_eq_u32 s14, 0x10100
	s_cbranch_scc0 .Lrt_loop
	v_cndmask_b32_e64 v0, v115, v0, s[6:7]
	ds_bpermute_b32 v1, v105, v0
	v_max_f32_e32 v5, v0, v0
	v_and_b32_e32 v7, 0x7fc, v90
	s_waitcnt lgkmcnt(0)
	v_max_f32_e32 v1, v1, v1
	v_max_f32_e32 v1, v5, v1
	ds_bpermute_b32 v5, v106, v1
	s_waitcnt lgkmcnt(0)
	v_max_f32_e32 v5, v5, v5
	v_max_f32_e32 v1, v1, v5
	ds_bpermute_b32 v5, v107, v1
	s_waitcnt lgkmcnt(0)
	v_max_f32_e32 v5, v5, v5
	v_max_f32_e32 v1, v1, v5
	ds_bpermute_b32 v5, v108, v1
	s_waitcnt lgkmcnt(0)
	v_max_f32_e32 v5, v5, v5
	v_max_f32_e32 v1, v1, v5
	ds_bpermute_b32 v1, v113, v1
	s_waitcnt lgkmcnt(0)
	v_sub_f32_e32 v0, v0, v1
	v_mul_f32_e32 v1, 0x3fb8aa3b, v0
	v_fma_f32 v5, v0, s27, -v1
	v_rndne_f32_e32 v6, v1
	v_fmac_f32_e32 v5, 0x32a5705f, v0
	v_sub_f32_e32 v1, v1, v6
	v_add_f32_e32 v1, v1, v5
	v_cvt_i32_f32_e32 v6, v6
	v_exp_f32_e32 v1, v1
	v_cmp_ngt_f32_e32 vcc, s30, v0
	v_ldexp_f32 v1, v1, v6
	s_nop 0
	v_cndmask_b32_e32 v1, 0, v1, vcc
	v_cmp_nlt_f32_e32 vcc, s31, v0
	s_nop 1
	v_cndmask_b32_e32 v5, v116, v1, vcc
	v_cndmask_b32_e64 v0, 0, v5, s[6:7]
	ds_bpermute_b32 v1, v105, v0
	s_waitcnt lgkmcnt(0)
	v_add_f32_e32 v0, v0, v1
	ds_bpermute_b32 v1, v106, v0
	s_waitcnt lgkmcnt(0)
	v_add_f32_e32 v0, v0, v1
	ds_bpermute_b32 v1, v107, v0
	s_waitcnt lgkmcnt(0)
	v_add_f32_e32 v1, v0, v1
	ds_bpermute_b32 v6, v108, v1
	v_lshl_add_u32 v0, v68, 4, v196
	v_lshlrev_b32_e32 v68, 2, v7
	s_waitcnt lgkmcnt(0)
	v_add_f32_e32 v1, v1, v6
	ds_bpermute_b32 v6, v113, v1
	v_ashrrev_i32_e32 v1, 31, v0
	v_lshlrev_b64 v[0:1], 13, v[0:1]
	v_lshl_add_u64 v[0:1], s[18:19], 0, v[0:1]
	s_and_saveexec_b64 s[14:15], s[6:7]
	s_cbranch_execz .LBB0_1026
	s_waitcnt lgkmcnt(0)
	v_div_scale_f32 v7, s[16:17], v6, v6, v5
	v_rcp_f32_e32 v8, v7
	v_div_scale_f32 v9, vcc, v5, v6, v5
	v_fma_f32 v10, -v7, v8, 1.0
	v_fmac_f32_e32 v8, v10, v8
	v_mul_f32_e32 v10, v9, v8
	v_fma_f32 v11, -v7, v10, v9
	v_fmac_f32_e32 v10, v11, v8
	v_fma_f32 v7, -v7, v10, v9
	v_div_fmas_f32 v7, v7, v8, v10
	v_div_fixup_f32 v5, v7, v6, v5
	v_lshl_add_u64 v[6:7], v[0:1], 0, v[68:69]
	global_store_dword v[6:7], v5, off
